# grid barrier: L1 invalidate (buffer_inv sc1) issued at arrival behind the arrival atomic instead of after the release (one workgroup per CU, only sc1 polls in between)
# speedup vs baseline: 1.0172x; 1.0148x over previous
.LBB0_238:
	s_or_b64 exec, exec, s[16:17]
	v_cvt_f32_u32_e32 v4, v2
	buffer_inv sc1
	s_waitcnt vmcnt(0)
	v_readfirstlane_b32 s3, v3
	v_sub_u32_e32 v3, 0, v2
	v_rcp_iflag_f32_e32 v4, v4
	v_add_u32_e32 v5, s3, v1
	v_mul_f32_e32 v4, 0x4f7ffffe, v4
	v_cvt_u32_f32_e32 v4, v4
	v_mul_lo_u32 v1, v3, v4
	v_mul_hi_u32 v1, v4, v1
	v_add_u32_e32 v1, v4, v1
	v_mul_hi_u32 v1, v5, v1
	v_mul_lo_u32 v3, v1, v2
	v_sub_u32_e32 v3, v5, v3
	v_add_u32_e32 v4, 1, v1
	v_cmp_ge_u32_e32 vcc, v3, v2
	s_nop 1
	v_cndmask_b32_e32 v1, v1, v4, vcc
	v_sub_u32_e32 v4, v3, v2
	v_cndmask_b32_e32 v3, v3, v4, vcc
	v_add_u32_e32 v4, 1, v1
	v_cmp_ge_u32_e32 vcc, v3, v2
	v_add_u32_e32 v3, 1, v5
	s_nop 0
	v_cndmask_b32_e32 v1, v1, v4, vcc
	v_mul_lo_u32 v4, v2, v1
	v_add_u32_e32 v2, v4, v2
	v_cmp_ne_u32_e32 vcc, v3, v2
	s_and_saveexec_b64 s[14:15], vcc
	s_xor_b64 s[14:15], exec, s[14:15]
	s_cbranch_execz .LBB0_252
	s_waitcnt lgkmcnt(0)
	v_mov_b32_e32 v0, 0x2000
	global_load_dword v0, v0, s[12:13] offset:1024 sc1
	s_add_u32 s18, s12, 0x2400
	s_addc_u32 s19, s13, 0
	s_waitcnt vmcnt(0)
	v_cmp_eq_u32_e32 vcc, v0, v1
	s_and_saveexec_b64 s[16:17], vcc
	s_cbranch_execz .LBB0_251
	s_mov_b32 s3, 1
	s_mov_b64 s[20:21], 0
	v_mov_b32_e32 v0, 0
	s_branch .LBB0_242

.LBB0_251:
	s_or_b64 exec, exec, s[16:17]
	s_waitcnt vmcnt(0)
	s_waitcnt vmcnt(0)

.LBB0_269:
	s_or_b64 exec, exec, s[10:11]
	s_mov_b64 s[10:11], exec
	v_mbcnt_lo_u32_b32 v0, s10, 0
	v_mbcnt_hi_u32_b32 v0, s11, v0
	v_cmp_eq_u32_e32 vcc, 0, v0
	s_waitcnt vmcnt(0)
	s_and_saveexec_b64 s[14:15], vcc
	s_cbranch_execz .LBB0_271
	s_bcnt1_i32_b64 s3, s[10:11]
	v_mov_b32_e32 v0, 0x2000
	v_mov_b32_e32 v1, s3
	global_atomic_add v0, v1, s[12:13] offset:1024

.LBB0_514:
	s_or_b64 exec, exec, s[12:13]
	v_cvt_f32_u32_e32 v4, v2
	buffer_inv sc1
	s_waitcnt vmcnt(0)
	v_readfirstlane_b32 s3, v3
	v_sub_u32_e32 v3, 0, v2
	v_rcp_iflag_f32_e32 v4, v4
	v_add_u32_e32 v5, s3, v1
	v_mul_f32_e32 v4, 0x4f7ffffe, v4
	v_cvt_u32_f32_e32 v4, v4
	v_mul_lo_u32 v1, v3, v4
	v_mul_hi_u32 v1, v4, v1
	v_add_u32_e32 v1, v4, v1
	v_mul_hi_u32 v1, v5, v1
	v_mul_lo_u32 v3, v1, v2
	v_sub_u32_e32 v3, v5, v3
	v_add_u32_e32 v4, 1, v1
	v_cmp_ge_u32_e32 vcc, v3, v2
	s_nop 1
	v_cndmask_b32_e32 v1, v1, v4, vcc
	v_sub_u32_e32 v4, v3, v2
	v_cndmask_b32_e32 v3, v3, v4, vcc
	v_add_u32_e32 v4, 1, v1
	v_cmp_ge_u32_e32 vcc, v3, v2
	v_add_u32_e32 v3, 1, v5
	s_nop 0
	v_cndmask_b32_e32 v1, v1, v4, vcc
	v_mul_lo_u32 v4, v2, v1
	v_add_u32_e32 v2, v4, v2
	v_cmp_ne_u32_e32 vcc, v3, v2
	s_and_saveexec_b64 s[10:11], vcc
	s_xor_b64 s[10:11], exec, s[10:11]
	s_cbranch_execz .LBB0_528
	s_waitcnt lgkmcnt(0)
	v_mov_b32_e32 v0, 0x2000
	global_load_dword v0, v0, s[8:9] offset:1024 sc1
	s_add_u32 s14, s8, 0x2400
	s_addc_u32 s15, s9, 0
	s_waitcnt vmcnt(0)
	v_cmp_eq_u32_e32 vcc, v0, v1
	s_and_saveexec_b64 s[12:13], vcc
	s_cbranch_execz .LBB0_527
	s_mov_b32 s3, 1
	s_mov_b64 s[16:17], 0
	v_mov_b32_e32 v0, 0
	s_branch .LBB0_518

.LBB0_527:
	s_or_b64 exec, exec, s[12:13]
	s_waitcnt vmcnt(0)
	s_waitcnt vmcnt(0)

.LBB0_545:
	s_or_b64 exec, exec, s[6:7]
	s_mov_b64 s[6:7], exec
	v_mbcnt_lo_u32_b32 v0, s6, 0
	v_mbcnt_hi_u32_b32 v0, s7, v0
	v_cmp_eq_u32_e32 vcc, 0, v0
	s_waitcnt vmcnt(0)
	s_and_saveexec_b64 s[10:11], vcc
	s_cbranch_execz .LBB0_547
	s_bcnt1_i32_b64 s3, s[6:7]
	v_mov_b32_e32 v0, 0x2000
	v_mov_b32_e32 v1, s3
	global_atomic_add v0, v1, s[8:9] offset:1024
